# mod items 48 columns wide (256 items, all workgroups busy); prompt attention builds its rel-pos bias table once per workgroup instead of once per item
# speedup vs baseline: 1.0006x; 1.0006x over previous
; #define LAS __attribute__((address_space(3)))
; __device__ __forceinline__ float siluf_(float x) { return x * __builtin_amdgcn_rcpf(1.f + __expf(-x)); }
; __device__ __forceinline__ void prologue_mod_item(const Args& a, LAS unsigned char* lds, int item, int tid) {
;     const int l = item / 96, n0 = (item % 96) * 64;
;     const float* W = a.in[9] + (size_t)l * DM * (6 * DM);
;     LAS float* sl = (LAS float*)lds;
;     const int col = tid & 63, kp = tid >> 6;
;     f32x2 acc[NSEQ / 2];
; #pragma unroll
;     for (int s = 0; s < NSEQ / 2; ++s) acc[s] = (f32x2){0.f, 0.f};
;     for (int half = 0; half < 2; ++half) {
;         __syncthreads();
;         for (int idx = tid; idx < 512 * NSEQ; idx += 512) { const int s = idx >> 9, kl = idx & 511, k = half * 512 + kl;
;             const float v = s < NPB ? a.in[6][s * DM + k] : a.in[7][(s - NPB) * DM + k];
;             sl[kl * NSEQ + s] = siluf_(v); }
;         __syncthreads();
; #pragma unroll 16
;         for (int kk = 0; kk < 64; ++kk) { const int kl = kp * 64 + kk;
;             const float w = __builtin_nontemporal_load(&W[(size_t)(half * 512 + kl) * (6 * DM) + n0 + col]);
;             const LAS f32x4* sp = (const LAS f32x4*)(sl + kl * NSEQ);
; #pragma unroll
;             for (int q = 0; q < NSEQ / 4; ++q) { const f32x4 sv = sp[q]; const f32x2 w2 = (f32x2){w, w};
;                 acc[2 * q] = __builtin_elementwise_fma((f32x2){sv[0], sv[1]}, w2, acc[2 * q]); acc[2 * q + 1] = __builtin_elementwise_fma((f32x2){sv[2], sv[3]}, w2, acc[2 * q + 1]); } }
.LBB0_104:
	s_cmpk_gt_i32 s52, 0xff
	s_cbranch_scc1 .LBB0_117
	v_and_b32_e32 v200, 63, v166
	v_lshrrev_b32_e32 v201, 6, v166
	v_and_b32_e32 v202, 15, v200
	v_lshrrev_b32_e32 v203, 4, v200
	v_readfirstlane_b32 s3, v201
	v_lshlrev_b32_e32 v204, 12, v202
	v_lshl_or_b32 v204, v201, 9, v204
	v_lshl_or_b32 v204, v203, 5, v204
	v_add_u32_e32 v205, 0x10000, v204
	v_lshl_add_u32 v206, v201, 4, v203
	v_mul_u32_u24_e32 v206, 0x30000, v206
	v_mul_u32_u24_e32 v212, 12, v202
	v_add_u32_e32 v206, v206, v212
	v_mul_u32_u24_e32 v212, 3, v202
	v_mad_u32_u24 v212, v201, 48, v212
	v_mul_u32_u24_e32 v212, 0xd0, v212
	v_lshl_add_u32 v207, v203, 4, v212
	v_mul_u32_u24_e32 v212, 0xd0, v200
	v_lshl_add_u32 v208, v201, 4, v212
	v_add_u32_e32 v209, 0x9c00, v208
	v_lshlrev_b32_e32 v210, 2, v200
	v_min_u32_e32 v213, 47, v200
	v_lshlrev_b32_e32 v44, 2, v213
	v_readlane_b32 s0, v252, 33
	v_readlane_b32 s1, v252, 34
	v_readlane_b32 s18, v252, 35
	v_readlane_b32 s19, v252, 36
	s_mov_b32 s15, s52
.Lmod_item:
	s_waitcnt vmcnt(0)
	s_lshr_b32 s16, s15, 7
	s_and_b32 s17, s15, 0x7f
	s_mul_i32 s17, s17, 192
	v_readlane_b32 s8, v252, 7
	v_readlane_b32 s9, v252, 8
	s_mul_i32 s6, s16, 0x1800000
	s_add_u32 s8, s8, s6
	s_addc_u32 s9, s9, 0
	s_add_u32 s8, s8, s17
	s_addc_u32 s9, s9, 0
	v_readlane_b32 s6, v252, 9
	v_readlane_b32 s7, v252, 10
	s_mul_i32 s14, s16, 0x6000
	s_add_u32 s6, s6, s14
	s_addc_u32 s7, s7, 0
	s_add_u32 s6, s6, s17
	s_addc_u32 s7, s7, 0
	s_mul_i32 s14, s16, 0x120000
	s_add_u32 s10, s26, 0x5400000
	s_addc_u32 s11, s27, 0
	s_add_u32 s10, s10, s14
	s_addc_u32 s11, s11, 0
	s_add_u32 s10, s10, s17
	s_addc_u32 s11, s11, 0
	s_mul_i32 s14, s3, 0x18000
	s_add_u32 s10, s10, s14
	s_addc_u32 s11, s11, 0
	global_load_dwordx4 v[120:123], v204, s[0:1]
	global_load_dwordx4 v[124:127], v204, s[0:1] offset:16
	global_load_dwordx4 v[128:131], v204, s[18:19]
	global_load_dwordx4 v[132:135], v204, s[18:19] offset:16
	global_load_dwordx4 v[136:139], v205, s[18:19]
	global_load_dwordx4 v[140:143], v205, s[18:19] offset:16
	global_load_dwordx3 v[168:170], v206, s[8:9] nt
	s_add_u32 s8, s8, 0x6000
	s_addc_u32 s9, s9, 0
	global_load_dwordx3 v[172:174], v206, s[8:9] nt
	s_add_u32 s8, s8, 0x6000
	s_addc_u32 s9, s9, 0
	global_load_dwordx3 v[176:178], v206, s[8:9] nt
	s_add_u32 s8, s8, 0x6000
	s_addc_u32 s9, s9, 0
	global_load_dwordx3 v[180:182], v206, s[8:9] nt
	s_add_u32 s8, s8, 0x6000
	s_addc_u32 s9, s9, 0
	global_load_dwordx3 v[184:186], v206, s[8:9] nt
	s_add_u32 s8, s8, 0x6000
	s_addc_u32 s9, s9, 0
	global_load_dwordx3 v[188:190], v206, s[8:9] nt
	s_add_u32 s8, s8, 0x6000
	s_addc_u32 s9, s9, 0
	global_load_dwordx3 v[192:194], v206, s[8:9] nt
	s_add_u32 s8, s8, 0x6000
	s_addc_u32 s9, s9, 0
	global_load_dwordx3 v[196:198], v206, s[8:9] nt
	s_add_u32 s8, s8, 0x96000
	s_addc_u32 s9, s9, 0
	global_load_dword v211, v44, s[6:7]
	global_load_dwordx4 v[148:151], v204, s[0:1] offset:128
	global_load_dwordx4 v[152:155], v204, s[0:1] offset:144
	global_load_dwordx4 v[156:159], v204, s[18:19] offset:128
	global_load_dwordx4 v[160:163], v204, s[18:19] offset:144
	global_load_dwordx4 v[34:37], v205, s[18:19] offset:128
	global_load_dwordx4 v[38:41], v205, s[18:19] offset:144
	global_load_dwordx3 v[216:218], v206, s[8:9] nt
	s_add_u32 s8, s8, 0x6000
	s_addc_u32 s9, s9, 0
	global_load_dwordx3 v[220:222], v206, s[8:9] nt
	s_add_u32 s8, s8, 0x6000
	s_addc_u32 s9, s9, 0
	global_load_dwordx3 v[224:226], v206, s[8:9] nt
	s_add_u32 s8, s8, 0x6000
	s_addc_u32 s9, s9, 0
	global_load_dwordx3 v[228:230], v206, s[8:9] nt
	s_add_u32 s8, s8, 0x6000
	s_addc_u32 s9, s9, 0
	global_load_dwordx3 v[232:234], v206, s[8:9] nt
	s_add_u32 s8, s8, 0x6000
	s_addc_u32 s9, s9, 0
	global_load_dwordx3 v[236:238], v206, s[8:9] nt
	s_add_u32 s8, s8, 0x6000
	s_addc_u32 s9, s9, 0
	global_load_dwordx3 v[240:242], v206, s[8:9] nt
	s_add_u32 s8, s8, 0x6000
	s_addc_u32 s9, s9, 0
	global_load_dwordx3 v[244:246], v206, s[8:9] nt
	s_add_u32 s8, s8, 0x96000
	s_addc_u32 s9, s9, 0
	s_waitcnt vmcnt(28)
	v_mul_f32_e32 v212, 0xbfb8aa3b, v120
	v_mul_f32_e32 v213, 0xbfb8aa3b, v121
	v_mul_f32_e32 v248, 0xbfb8aa3b, v122
	v_mul_f32_e32 v249, 0xbfb8aa3b, v123
	v_exp_f32_e32 v212, v212
	v_exp_f32_e32 v213, v213
	v_exp_f32_e32 v248, v248
	v_exp_f32_e32 v249, v249
	v_add_f32_e32 v212, 1.0, v212
	v_add_f32_e32 v213, 1.0, v213
	v_add_f32_e32 v248, 1.0, v248
	v_add_f32_e32 v249, 1.0, v249
	v_rcp_f32_e32 v212, v212
	v_rcp_f32_e32 v213, v213
	v_rcp_f32_e32 v248, v248
	v_rcp_f32_e32 v249, v249
	v_mul_f32_e32 v120, v120, v212
	v_mul_f32_e32 v121, v121, v213
	v_mul_f32_e32 v122, v122, v248
	v_mul_f32_e32 v123, v123, v249
	s_waitcnt vmcnt(27)
	v_mul_f32_e32 v212, 0xbfb8aa3b, v124
	v_mul_f32_e32 v213, 0xbfb8aa3b, v125
	v_mul_f32_e32 v248, 0xbfb8aa3b, v126
	v_mul_f32_e32 v249, 0xbfb8aa3b, v127
	v_exp_f32_e32 v212, v212
	v_exp_f32_e32 v213, v213
	v_exp_f32_e32 v248, v248
	v_exp_f32_e32 v249, v249
	v_add_f32_e32 v212, 1.0, v212
	v_add_f32_e32 v213, 1.0, v213
	v_add_f32_e32 v248, 1.0, v248
	v_add_f32_e32 v249, 1.0, v249
	v_rcp_f32_e32 v212, v212
	v_rcp_f32_e32 v213, v213
	v_rcp_f32_e32 v248, v248
	v_rcp_f32_e32 v249, v249
	v_mul_f32_e32 v124, v124, v212
	v_mul_f32_e32 v125, v125, v213
	v_mul_f32_e32 v126, v126, v248
	v_mul_f32_e32 v127, v127, v249
	s_waitcnt vmcnt(26)
	v_mul_f32_e32 v212, 0xbfb8aa3b, v128
	v_mul_f32_e32 v213, 0xbfb8aa3b, v129
	v_mul_f32_e32 v248, 0xbfb8aa3b, v130
	v_mul_f32_e32 v249, 0xbfb8aa3b, v131
	v_exp_f32_e32 v212, v212
	v_exp_f32_e32 v213, v213
	v_exp_f32_e32 v248, v248
	v_exp_f32_e32 v249, v249
	v_add_f32_e32 v212, 1.0, v212
	v_add_f32_e32 v213, 1.0, v213
	v_add_f32_e32 v248, 1.0, v248
	v_add_f32_e32 v249, 1.0, v249
	v_rcp_f32_e32 v212, v212
	v_rcp_f32_e32 v213, v213
	v_rcp_f32_e32 v248, v248
	v_rcp_f32_e32 v249, v249
	v_mul_f32_e32 v128, v128, v212
	v_mul_f32_e32 v129, v129, v213
	v_mul_f32_e32 v130, v130, v248
	v_mul_f32_e32 v131, v131, v249
	s_waitcnt vmcnt(25)
; #define LAS __attribute__((address_space(3)))
; __device__ __forceinline__ float siluf_(float x) { return x * __builtin_amdgcn_rcpf(1.f + __expf(-x)); }
; __device__ __forceinline__ void prologue_mod_item(const Args& a, LAS unsigned char* lds, int item, int tid) {
;     ...
;         for (int idx = tid; idx < 512 * NSEQ; idx += 512) { const int s = idx >> 9, kl = idx & 511, k = half * 512 + kl;
;             const float v = s < NPB ? a.in[6][s * DM + k] : a.in[7][(s - NPB) * DM + k];
;             sl[kl * NSEQ + s] = siluf_(v); }
;         __syncthreads();
; #pragma unroll 16
;         for (int kk = 0; kk < 64; ++kk) { const int kl = kp * 64 + kk;
;             const float w = __builtin_nontemporal_load(&W[(size_t)(half * 512 + kl) * (6 * DM) + n0 + col]);
;             const LAS f32x4* sp = (const LAS f32x4*)(sl + kl * NSEQ);
; #pragma unroll
;             for (int q = 0; q < NSEQ / 4; ++q) { const f32x4 sv = sp[q]; const f32x2 w2 = (f32x2){w, w};
;                 acc[2 * q] = __builtin_elementwise_fma((f32x2){sv[0], sv[1]}, w2, acc[2 * q]); acc[2 * q + 1] = __builtin_elementwise_fma((f32x2){sv[2], sv[3]}, w2, acc[2 * q + 1]); } }
	v_mul_f32_e32 v212, 0xbfb8aa3b, v132
	v_mul_f32_e32 v213, 0xbfb8aa3b, v133
	v_mul_f32_e32 v248, 0xbfb8aa3b, v134
	v_mul_f32_e32 v249, 0xbfb8aa3b, v135
	v_exp_f32_e32 v212, v212
	v_exp_f32_e32 v213, v213
	v_exp_f32_e32 v248, v248
	v_exp_f32_e32 v249, v249
	v_add_f32_e32 v212, 1.0, v212
	v_add_f32_e32 v213, 1.0, v213
	v_add_f32_e32 v248, 1.0, v248
	v_add_f32_e32 v249, 1.0, v249
	v_rcp_f32_e32 v212, v212
	v_rcp_f32_e32 v213, v213
	v_rcp_f32_e32 v248, v248
	v_rcp_f32_e32 v249, v249
	v_mul_f32_e32 v132, v132, v212
	v_mul_f32_e32 v133, v133, v213
	v_mul_f32_e32 v134, v134, v248
	v_mul_f32_e32 v135, v135, v249
	s_waitcnt vmcnt(24)
	v_mul_f32_e32 v212, 0xbfb8aa3b, v136
	v_mul_f32_e32 v213, 0xbfb8aa3b, v137
	v_mul_f32_e32 v248, 0xbfb8aa3b, v138
	v_mul_f32_e32 v249, 0xbfb8aa3b, v139
	v_exp_f32_e32 v212, v212
	v_exp_f32_e32 v213, v213
	v_exp_f32_e32 v248, v248
	v_exp_f32_e32 v249, v249
	v_add_f32_e32 v212, 1.0, v212
	v_add_f32_e32 v213, 1.0, v213
	v_add_f32_e32 v248, 1.0, v248
	v_add_f32_e32 v249, 1.0, v249
	v_rcp_f32_e32 v212, v212
	v_rcp_f32_e32 v213, v213
	v_rcp_f32_e32 v248, v248
	v_rcp_f32_e32 v249, v249
	v_mul_f32_e32 v136, v136, v212
	v_mul_f32_e32 v137, v137, v213
	v_mul_f32_e32 v138, v138, v248
	v_mul_f32_e32 v139, v139, v249
	s_waitcnt vmcnt(23)
	v_mul_f32_e32 v212, 0xbfb8aa3b, v140
	v_mul_f32_e32 v213, 0xbfb8aa3b, v141
	v_mul_f32_e32 v248, 0xbfb8aa3b, v142
	v_mul_f32_e32 v249, 0xbfb8aa3b, v143
	v_exp_f32_e32 v212, v212
	v_exp_f32_e32 v213, v213
	v_exp_f32_e32 v248, v248
	v_exp_f32_e32 v249, v249
	v_add_f32_e32 v212, 1.0, v212
	v_add_f32_e32 v213, 1.0, v213
	v_add_f32_e32 v248, 1.0, v248
	v_add_f32_e32 v249, 1.0, v249
	v_rcp_f32_e32 v212, v212
	v_rcp_f32_e32 v213, v213
	v_rcp_f32_e32 v248, v248
	v_rcp_f32_e32 v249, v249
	v_mul_f32_e32 v140, v140, v212
	v_mul_f32_e32 v141, v141, v213
	v_mul_f32_e32 v142, v142, v248
	v_mul_f32_e32 v143, v143, v249
	s_waitcnt vmcnt(22)
	v_mfma_f32_16x16x4_f32 v[62:65], v120, v168, 0
	v_mfma_f32_16x16x4_f32 v[66:69], v120, v169, 0
	v_mfma_f32_16x16x4_f32 v[70:73], v120, v170, 0
	v_mfma_f32_16x16x4_f32 v[78:81], v128, v168, 0
	v_mfma_f32_16x16x4_f32 v[82:85], v128, v169, 0
	v_mfma_f32_16x16x4_f32 v[86:89], v128, v170, 0
	v_mfma_f32_16x16x4_f32 v[98:101], v136, v168, 0
	v_mfma_f32_16x16x4_f32 v[102:105], v136, v169, 0
	v_mfma_f32_16x16x4_f32 v[106:109], v136, v170, 0
	s_waitcnt vmcnt(21)
	v_mfma_f32_16x16x4_f32 v[62:65], v121, v172, v[62:65]
	v_mfma_f32_16x16x4_f32 v[66:69], v121, v173, v[66:69]
	v_mfma_f32_16x16x4_f32 v[70:73], v121, v174, v[70:73]
	v_mfma_f32_16x16x4_f32 v[78:81], v129, v172, v[78:81]
	v_mfma_f32_16x16x4_f32 v[82:85], v129, v173, v[82:85]
	v_mfma_f32_16x16x4_f32 v[86:89], v129, v174, v[86:89]
	v_mfma_f32_16x16x4_f32 v[98:101], v137, v172, v[98:101]
	v_mfma_f32_16x16x4_f32 v[102:105], v137, v173, v[102:105]
	v_mfma_f32_16x16x4_f32 v[106:109], v137, v174, v[106:109]
	s_waitcnt vmcnt(20)
	v_mfma_f32_16x16x4_f32 v[62:65], v122, v176, v[62:65]
	v_mfma_f32_16x16x4_f32 v[66:69], v122, v177, v[66:69]
	v_mfma_f32_16x16x4_f32 v[70:73], v122, v178, v[70:73]
	v_mfma_f32_16x16x4_f32 v[78:81], v130, v176, v[78:81]
	v_mfma_f32_16x16x4_f32 v[82:85], v130, v177, v[82:85]
	v_mfma_f32_16x16x4_f32 v[86:89], v130, v178, v[86:89]
	v_mfma_f32_16x16x4_f32 v[98:101], v138, v176, v[98:101]
	v_mfma_f32_16x16x4_f32 v[102:105], v138, v177, v[102:105]
	v_mfma_f32_16x16x4_f32 v[106:109], v138, v178, v[106:109]
	s_waitcnt vmcnt(19)
	v_mfma_f32_16x16x4_f32 v[62:65], v123, v180, v[62:65]
	v_mfma_f32_16x16x4_f32 v[66:69], v123, v181, v[66:69]
	v_mfma_f32_16x16x4_f32 v[70:73], v123, v182, v[70:73]
	v_mfma_f32_16x16x4_f32 v[78:81], v131, v180, v[78:81]
	v_mfma_f32_16x16x4_f32 v[82:85], v131, v181, v[82:85]
	v_mfma_f32_16x16x4_f32 v[86:89], v131, v182, v[86:89]
	v_mfma_f32_16x16x4_f32 v[98:101], v139, v180, v[98:101]
	v_mfma_f32_16x16x4_f32 v[102:105], v139, v181, v[102:105]
	v_mfma_f32_16x16x4_f32 v[106:109], v139, v182, v[106:109]
	s_waitcnt vmcnt(18)
	v_mfma_f32_16x16x4_f32 v[62:65], v124, v184, v[62:65]
	v_mfma_f32_16x16x4_f32 v[66:69], v124, v185, v[66:69]
	v_mfma_f32_16x16x4_f32 v[70:73], v124, v186, v[70:73]
	v_mfma_f32_16x16x4_f32 v[78:81], v132, v184, v[78:81]
	v_mfma_f32_16x16x4_f32 v[82:85], v132, v185, v[82:85]
	v_mfma_f32_16x16x4_f32 v[86:89], v132, v186, v[86:89]
	v_mfma_f32_16x16x4_f32 v[98:101], v140, v184, v[98:101]
	v_mfma_f32_16x16x4_f32 v[102:105], v140, v185, v[102:105]
	v_mfma_f32_16x16x4_f32 v[106:109], v140, v186, v[106:109]
	s_waitcnt vmcnt(17)
	v_mfma_f32_16x16x4_f32 v[62:65], v125, v188, v[62:65]
	v_mfma_f32_16x16x4_f32 v[66:69], v125, v189, v[66:69]
	v_mfma_f32_16x16x4_f32 v[70:73], v125, v190, v[70:73]
	v_mfma_f32_16x16x4_f32 v[78:81], v133, v188, v[78:81]
	v_mfma_f32_16x16x4_f32 v[82:85], v133, v189, v[82:85]
	v_mfma_f32_16x16x4_f32 v[86:89], v133, v190, v[86:89]
	v_mfma_f32_16x16x4_f32 v[98:101], v141, v188, v[98:101]
	v_mfma_f32_16x16x4_f32 v[102:105], v141, v189, v[102:105]
	v_mfma_f32_16x16x4_f32 v[106:109], v141, v190, v[106:109]
	s_waitcnt vmcnt(16)
	v_mfma_f32_16x16x4_f32 v[62:65], v126, v192, v[62:65]
	v_mfma_f32_16x16x4_f32 v[66:69], v126, v193, v[66:69]
	v_mfma_f32_16x16x4_f32 v[70:73], v126, v194, v[70:73]
	v_mfma_f32_16x16x4_f32 v[78:81], v134, v192, v[78:81]
	v_mfma_f32_16x16x4_f32 v[82:85], v134, v193, v[82:85]
	v_mfma_f32_16x16x4_f32 v[86:89], v134, v194, v[86:89]
	v_mfma_f32_16x16x4_f32 v[98:101], v142, v192, v[98:101]
	v_mfma_f32_16x16x4_f32 v[102:105], v142, v193, v[102:105]
	v_mfma_f32_16x16x4_f32 v[106:109], v142, v194, v[106:109]
	s_waitcnt vmcnt(15)
; #define LAS __attribute__((address_space(3)))
; __device__ __forceinline__ float siluf_(float x) { return x * __builtin_amdgcn_rcpf(1.f + __expf(-x)); }
; __device__ __forceinline__ void prologue_mod_item(const Args& a, LAS unsigned char* lds, int item, int tid) {
;     ...
;         for (int idx = tid; idx < 512 * NSEQ; idx += 512) { const int s = idx >> 9, kl = idx & 511, k = half * 512 + kl;
;             const float v = s < NPB ? a.in[6][s * DM + k] : a.in[7][(s - NPB) * DM + k];
;             sl[kl * NSEQ + s] = siluf_(v); }
;         __syncthreads();
; #pragma unroll 16
;         for (int kk = 0; kk < 64; ++kk) { const int kl = kp * 64 + kk;
;             const float w = __builtin_nontemporal_load(&W[(size_t)(half * 512 + kl) * (6 * DM) + n0 + col]);
;             const LAS f32x4* sp = (const LAS f32x4*)(sl + kl * NSEQ);
; #pragma unroll
;             for (int q = 0; q < NSEQ / 4; ++q) { const f32x4 sv = sp[q]; const f32x2 w2 = (f32x2){w, w};
;                 acc[2 * q] = __builtin_elementwise_fma((f32x2){sv[0], sv[1]}, w2, acc[2 * q]); acc[2 * q + 1] = __builtin_elementwise_fma((f32x2){sv[2], sv[3]}, w2, acc[2 * q + 1]); } }
	v_mfma_f32_16x16x4_f32 v[62:65], v127, v196, v[62:65]
	v_mfma_f32_16x16x4_f32 v[66:69], v127, v197, v[66:69]
	v_mfma_f32_16x16x4_f32 v[70:73], v127, v198, v[70:73]
	v_mfma_f32_16x16x4_f32 v[78:81], v135, v196, v[78:81]
	v_mfma_f32_16x16x4_f32 v[82:85], v135, v197, v[82:85]
	v_mfma_f32_16x16x4_f32 v[86:89], v135, v198, v[86:89]
	v_mfma_f32_16x16x4_f32 v[98:101], v143, v196, v[98:101]
	v_mfma_f32_16x16x4_f32 v[102:105], v143, v197, v[102:105]
	v_mfma_f32_16x16x4_f32 v[106:109], v143, v198, v[106:109]
	global_load_dwordx4 v[120:123], v204, s[0:1] offset:256
	global_load_dwordx4 v[124:127], v204, s[0:1] offset:272
	global_load_dwordx4 v[128:131], v204, s[18:19] offset:256
	global_load_dwordx4 v[132:135], v204, s[18:19] offset:272
	global_load_dwordx4 v[136:139], v205, s[18:19] offset:256
	global_load_dwordx4 v[140:143], v205, s[18:19] offset:272
	global_load_dwordx3 v[168:170], v206, s[8:9] nt
	s_add_u32 s8, s8, 0x6000
	s_addc_u32 s9, s9, 0
	global_load_dwordx3 v[172:174], v206, s[8:9] nt
	s_add_u32 s8, s8, 0x6000
	s_addc_u32 s9, s9, 0
	global_load_dwordx3 v[176:178], v206, s[8:9] nt
	s_add_u32 s8, s8, 0x6000
	s_addc_u32 s9, s9, 0
	global_load_dwordx3 v[180:182], v206, s[8:9] nt
	s_add_u32 s8, s8, 0x6000
	s_addc_u32 s9, s9, 0
	global_load_dwordx3 v[184:186], v206, s[8:9] nt
	s_add_u32 s8, s8, 0x6000
	s_addc_u32 s9, s9, 0
	global_load_dwordx3 v[188:190], v206, s[8:9] nt
	s_add_u32 s8, s8, 0x6000
	s_addc_u32 s9, s9, 0
	global_load_dwordx3 v[192:194], v206, s[8:9] nt
	s_add_u32 s8, s8, 0x6000
	s_addc_u32 s9, s9, 0
	global_load_dwordx3 v[196:198], v206, s[8:9] nt
	s_add_u32 s8, s8, 0x96000
	s_addc_u32 s9, s9, 0
	s_waitcnt vmcnt(27)
	v_mul_f32_e32 v212, 0xbfb8aa3b, v148
	v_mul_f32_e32 v213, 0xbfb8aa3b, v149
	v_mul_f32_e32 v248, 0xbfb8aa3b, v150
	v_mul_f32_e32 v249, 0xbfb8aa3b, v151
	v_exp_f32_e32 v212, v212
	v_exp_f32_e32 v213, v213
	v_exp_f32_e32 v248, v248
	v_exp_f32_e32 v249, v249
	v_add_f32_e32 v212, 1.0, v212
	v_add_f32_e32 v213, 1.0, v213
	v_add_f32_e32 v248, 1.0, v248
	v_add_f32_e32 v249, 1.0, v249
	v_rcp_f32_e32 v212, v212
	v_rcp_f32_e32 v213, v213
	v_rcp_f32_e32 v248, v248
	v_rcp_f32_e32 v249, v249
	v_mul_f32_e32 v148, v148, v212
	v_mul_f32_e32 v149, v149, v213
	v_mul_f32_e32 v150, v150, v248
	v_mul_f32_e32 v151, v151, v249
	s_waitcnt vmcnt(26)
	v_mul_f32_e32 v212, 0xbfb8aa3b, v152
	v_mul_f32_e32 v213, 0xbfb8aa3b, v153
	v_mul_f32_e32 v248, 0xbfb8aa3b, v154
	v_mul_f32_e32 v249, 0xbfb8aa3b, v155
	v_exp_f32_e32 v212, v212
	v_exp_f32_e32 v213, v213
	v_exp_f32_e32 v248, v248
	v_exp_f32_e32 v249, v249
	v_add_f32_e32 v212, 1.0, v212
	v_add_f32_e32 v213, 1.0, v213
	v_add_f32_e32 v248, 1.0, v248
	v_add_f32_e32 v249, 1.0, v249
	v_rcp_f32_e32 v212, v212
	v_rcp_f32_e32 v213, v213
	v_rcp_f32_e32 v248, v248
	v_rcp_f32_e32 v249, v249
	v_mul_f32_e32 v152, v152, v212
	v_mul_f32_e32 v153, v153, v213
	v_mul_f32_e32 v154, v154, v248
	v_mul_f32_e32 v155, v155, v249
	s_waitcnt vmcnt(25)
	v_mul_f32_e32 v212, 0xbfb8aa3b, v156
	v_mul_f32_e32 v213, 0xbfb8aa3b, v157
	v_mul_f32_e32 v248, 0xbfb8aa3b, v158
	v_mul_f32_e32 v249, 0xbfb8aa3b, v159
	v_exp_f32_e32 v212, v212
	v_exp_f32_e32 v213, v213
	v_exp_f32_e32 v248, v248
	v_exp_f32_e32 v249, v249
	v_add_f32_e32 v212, 1.0, v212
	v_add_f32_e32 v213, 1.0, v213
	v_add_f32_e32 v248, 1.0, v248
	v_add_f32_e32 v249, 1.0, v249
	v_rcp_f32_e32 v212, v212
	v_rcp_f32_e32 v213, v213
	v_rcp_f32_e32 v248, v248
	v_rcp_f32_e32 v249, v249
	v_mul_f32_e32 v156, v156, v212
	v_mul_f32_e32 v157, v157, v213
	v_mul_f32_e32 v158, v158, v248
	v_mul_f32_e32 v159, v159, v249
	s_waitcnt vmcnt(24)
	v_mul_f32_e32 v212, 0xbfb8aa3b, v160
	v_mul_f32_e32 v213, 0xbfb8aa3b, v161
	v_mul_f32_e32 v248, 0xbfb8aa3b, v162
	v_mul_f32_e32 v249, 0xbfb8aa3b, v163
	v_exp_f32_e32 v212, v212
	v_exp_f32_e32 v213, v213
	v_exp_f32_e32 v248, v248
	v_exp_f32_e32 v249, v249
	v_add_f32_e32 v212, 1.0, v212
	v_add_f32_e32 v213, 1.0, v213
	v_add_f32_e32 v248, 1.0, v248
	v_add_f32_e32 v249, 1.0, v249
	v_rcp_f32_e32 v212, v212
	v_rcp_f32_e32 v213, v213
	v_rcp_f32_e32 v248, v248
	v_rcp_f32_e32 v249, v249
	v_mul_f32_e32 v160, v160, v212
	v_mul_f32_e32 v161, v161, v213
	v_mul_f32_e32 v162, v162, v248
	v_mul_f32_e32 v163, v163, v249
	s_waitcnt vmcnt(23)
	v_mul_f32_e32 v212, 0xbfb8aa3b, v34
	v_mul_f32_e32 v213, 0xbfb8aa3b, v35
	v_mul_f32_e32 v248, 0xbfb8aa3b, v36
	v_mul_f32_e32 v249, 0xbfb8aa3b, v37
	v_exp_f32_e32 v212, v212
	v_exp_f32_e32 v213, v213
	v_exp_f32_e32 v248, v248
	v_exp_f32_e32 v249, v249
	v_add_f32_e32 v212, 1.0, v212
	v_add_f32_e32 v213, 1.0, v213
	v_add_f32_e32 v248, 1.0, v248
	v_add_f32_e32 v249, 1.0, v249
	v_rcp_f32_e32 v212, v212
	v_rcp_f32_e32 v213, v213
	v_rcp_f32_e32 v248, v248
	v_rcp_f32_e32 v249, v249
	v_mul_f32_e32 v34, v34, v212
	v_mul_f32_e32 v35, v35, v213
	v_mul_f32_e32 v36, v36, v248
	v_mul_f32_e32 v37, v37, v249
	s_waitcnt vmcnt(22)
	v_mul_f32_e32 v212, 0xbfb8aa3b, v38
	v_mul_f32_e32 v213, 0xbfb8aa3b, v39
	v_mul_f32_e32 v248, 0xbfb8aa3b, v40
	v_mul_f32_e32 v249, 0xbfb8aa3b, v41
	v_exp_f32_e32 v212, v212
	v_exp_f32_e32 v213, v213
	v_exp_f32_e32 v248, v248
	v_exp_f32_e32 v249, v249
	v_add_f32_e32 v212, 1.0, v212
	v_add_f32_e32 v213, 1.0, v213
	v_add_f32_e32 v248, 1.0, v248
	v_add_f32_e32 v249, 1.0, v249
	v_rcp_f32_e32 v212, v212
	v_rcp_f32_e32 v213, v213
	v_rcp_f32_e32 v248, v248
	v_rcp_f32_e32 v249, v249
	v_mul_f32_e32 v38, v38, v212
	v_mul_f32_e32 v39, v39, v213
	v_mul_f32_e32 v40, v40, v248
	v_mul_f32_e32 v41, v41, v249
	s_waitcnt vmcnt(21)
; #define LAS __attribute__((address_space(3)))
; __device__ __forceinline__ float siluf_(float x) { return x * __builtin_amdgcn_rcpf(1.f + __expf(-x)); }
; __device__ __forceinline__ void prologue_mod_item(const Args& a, LAS unsigned char* lds, int item, int tid) {
;     ...
;         for (int idx = tid; idx < 512 * NSEQ; idx += 512) { const int s = idx >> 9, kl = idx & 511, k = half * 512 + kl;
;             const float v = s < NPB ? a.in[6][s * DM + k] : a.in[7][(s - NPB) * DM + k];
;             sl[kl * NSEQ + s] = siluf_(v); }
;         __syncthreads();
; #pragma unroll 16
;         for (int kk = 0; kk < 64; ++kk) { const int kl = kp * 64 + kk;
;             const float w = __builtin_nontemporal_load(&W[(size_t)(half * 512 + kl) * (6 * DM) + n0 + col]);
;             const LAS f32x4* sp = (const LAS f32x4*)(sl + kl * NSEQ);
; #pragma unroll
;             for (int q = 0; q < NSEQ / 4; ++q) { const f32x4 sv = sp[q]; const f32x2 w2 = (f32x2){w, w};
;                 acc[2 * q] = __builtin_elementwise_fma((f32x2){sv[0], sv[1]}, w2, acc[2 * q]); acc[2 * q + 1] = __builtin_elementwise_fma((f32x2){sv[2], sv[3]}, w2, acc[2 * q + 1]); } }
	v_mfma_f32_16x16x4_f32 v[62:65], v148, v216, v[62:65]
	v_mfma_f32_16x16x4_f32 v[66:69], v148, v217, v[66:69]
	v_mfma_f32_16x16x4_f32 v[70:73], v148, v218, v[70:73]
	v_mfma_f32_16x16x4_f32 v[78:81], v156, v216, v[78:81]
	v_mfma_f32_16x16x4_f32 v[82:85], v156, v217, v[82:85]
	v_mfma_f32_16x16x4_f32 v[86:89], v156, v218, v[86:89]
	v_mfma_f32_16x16x4_f32 v[98:101], v34, v216, v[98:101]
	v_mfma_f32_16x16x4_f32 v[102:105], v34, v217, v[102:105]
	v_mfma_f32_16x16x4_f32 v[106:109], v34, v218, v[106:109]
	s_waitcnt vmcnt(20)
	v_mfma_f32_16x16x4_f32 v[62:65], v149, v220, v[62:65]
	v_mfma_f32_16x16x4_f32 v[66:69], v149, v221, v[66:69]
	v_mfma_f32_16x16x4_f32 v[70:73], v149, v222, v[70:73]
	v_mfma_f32_16x16x4_f32 v[78:81], v157, v220, v[78:81]
	v_mfma_f32_16x16x4_f32 v[82:85], v157, v221, v[82:85]
	v_mfma_f32_16x16x4_f32 v[86:89], v157, v222, v[86:89]
	v_mfma_f32_16x16x4_f32 v[98:101], v35, v220, v[98:101]
	v_mfma_f32_16x16x4_f32 v[102:105], v35, v221, v[102:105]
	v_mfma_f32_16x16x4_f32 v[106:109], v35, v222, v[106:109]
	s_waitcnt vmcnt(19)
	v_mfma_f32_16x16x4_f32 v[62:65], v150, v224, v[62:65]
	v_mfma_f32_16x16x4_f32 v[66:69], v150, v225, v[66:69]
	v_mfma_f32_16x16x4_f32 v[70:73], v150, v226, v[70:73]
	v_mfma_f32_16x16x4_f32 v[78:81], v158, v224, v[78:81]
	v_mfma_f32_16x16x4_f32 v[82:85], v158, v225, v[82:85]
	v_mfma_f32_16x16x4_f32 v[86:89], v158, v226, v[86:89]
	v_mfma_f32_16x16x4_f32 v[98:101], v36, v224, v[98:101]
	v_mfma_f32_16x16x4_f32 v[102:105], v36, v225, v[102:105]
	v_mfma_f32_16x16x4_f32 v[106:109], v36, v226, v[106:109]
	s_waitcnt vmcnt(18)
	v_mfma_f32_16x16x4_f32 v[62:65], v151, v228, v[62:65]
	v_mfma_f32_16x16x4_f32 v[66:69], v151, v229, v[66:69]
	v_mfma_f32_16x16x4_f32 v[70:73], v151, v230, v[70:73]
	v_mfma_f32_16x16x4_f32 v[78:81], v159, v228, v[78:81]
	v_mfma_f32_16x16x4_f32 v[82:85], v159, v229, v[82:85]
	v_mfma_f32_16x16x4_f32 v[86:89], v159, v230, v[86:89]
	v_mfma_f32_16x16x4_f32 v[98:101], v37, v228, v[98:101]
	v_mfma_f32_16x16x4_f32 v[102:105], v37, v229, v[102:105]
	v_mfma_f32_16x16x4_f32 v[106:109], v37, v230, v[106:109]
	s_waitcnt vmcnt(17)
	v_mfma_f32_16x16x4_f32 v[62:65], v152, v232, v[62:65]
	v_mfma_f32_16x16x4_f32 v[66:69], v152, v233, v[66:69]
	v_mfma_f32_16x16x4_f32 v[70:73], v152, v234, v[70:73]
	v_mfma_f32_16x16x4_f32 v[78:81], v160, v232, v[78:81]
	v_mfma_f32_16x16x4_f32 v[82:85], v160, v233, v[82:85]
	v_mfma_f32_16x16x4_f32 v[86:89], v160, v234, v[86:89]
	v_mfma_f32_16x16x4_f32 v[98:101], v38, v232, v[98:101]
	v_mfma_f32_16x16x4_f32 v[102:105], v38, v233, v[102:105]
	v_mfma_f32_16x16x4_f32 v[106:109], v38, v234, v[106:109]
	s_waitcnt vmcnt(16)
	v_mfma_f32_16x16x4_f32 v[62:65], v153, v236, v[62:65]
	v_mfma_f32_16x16x4_f32 v[66:69], v153, v237, v[66:69]
	v_mfma_f32_16x16x4_f32 v[70:73], v153, v238, v[70:73]
	v_mfma_f32_16x16x4_f32 v[78:81], v161, v236, v[78:81]
	v_mfma_f32_16x16x4_f32 v[82:85], v161, v237, v[82:85]
	v_mfma_f32_16x16x4_f32 v[86:89], v161, v238, v[86:89]
	v_mfma_f32_16x16x4_f32 v[98:101], v39, v236, v[98:101]
	v_mfma_f32_16x16x4_f32 v[102:105], v39, v237, v[102:105]
	v_mfma_f32_16x16x4_f32 v[106:109], v39, v238, v[106:109]
	s_waitcnt vmcnt(15)
	v_mfma_f32_16x16x4_f32 v[62:65], v154, v240, v[62:65]
	v_mfma_f32_16x16x4_f32 v[66:69], v154, v241, v[66:69]
	v_mfma_f32_16x16x4_f32 v[70:73], v154, v242, v[70:73]
	v_mfma_f32_16x16x4_f32 v[78:81], v162, v240, v[78:81]
	v_mfma_f32_16x16x4_f32 v[82:85], v162, v241, v[82:85]
	v_mfma_f32_16x16x4_f32 v[86:89], v162, v242, v[86:89]
	v_mfma_f32_16x16x4_f32 v[98:101], v40, v240, v[98:101]
	v_mfma_f32_16x16x4_f32 v[102:105], v40, v241, v[102:105]
	v_mfma_f32_16x16x4_f32 v[106:109], v40, v242, v[106:109]
	s_waitcnt vmcnt(14)
	v_mfma_f32_16x16x4_f32 v[62:65], v155, v244, v[62:65]
	v_mfma_f32_16x16x4_f32 v[66:69], v155, v245, v[66:69]
	v_mfma_f32_16x16x4_f32 v[70:73], v155, v246, v[70:73]
	v_mfma_f32_16x16x4_f32 v[78:81], v163, v244, v[78:81]
	v_mfma_f32_16x16x4_f32 v[82:85], v163, v245, v[82:85]
	v_mfma_f32_16x16x4_f32 v[86:89], v163, v246, v[86:89]
	v_mfma_f32_16x16x4_f32 v[98:101], v41, v244, v[98:101]
	v_mfma_f32_16x16x4_f32 v[102:105], v41, v245, v[102:105]
	v_mfma_f32_16x16x4_f32 v[106:109], v41, v246, v[106:109]
	global_load_dwordx4 v[148:151], v204, s[0:1] offset:384
	global_load_dwordx4 v[152:155], v204, s[0:1] offset:400
	global_load_dwordx4 v[156:159], v204, s[18:19] offset:384
	global_load_dwordx4 v[160:163], v204, s[18:19] offset:400
	global_load_dwordx4 v[34:37], v205, s[18:19] offset:384
	global_load_dwordx4 v[38:41], v205, s[18:19] offset:400
	global_load_dwordx3 v[216:218], v206, s[8:9] nt
	s_add_u32 s8, s8, 0x6000
	s_addc_u32 s9, s9, 0
	global_load_dwordx3 v[220:222], v206, s[8:9] nt
	s_add_u32 s8, s8, 0x6000
	s_addc_u32 s9, s9, 0
	global_load_dwordx3 v[224:226], v206, s[8:9] nt
	s_add_u32 s8, s8, 0x6000
	s_addc_u32 s9, s9, 0
	global_load_dwordx3 v[228:230], v206, s[8:9] nt
	s_add_u32 s8, s8, 0x6000
	s_addc_u32 s9, s9, 0
	global_load_dwordx3 v[232:234], v206, s[8:9] nt
	s_add_u32 s8, s8, 0x6000
	s_addc_u32 s9, s9, 0
	global_load_dwordx3 v[236:238], v206, s[8:9] nt
	s_add_u32 s8, s8, 0x6000
	s_addc_u32 s9, s9, 0
	global_load_dwordx3 v[240:242], v206, s[8:9] nt
	s_add_u32 s8, s8, 0x6000
	s_addc_u32 s9, s9, 0
	global_load_dwordx3 v[244:246], v206, s[8:9] nt
	s_add_u32 s8, s8, 0x96000
	s_addc_u32 s9, s9, 0
	s_waitcnt vmcnt(27)
	v_mul_f32_e32 v212, 0xbfb8aa3b, v120
	v_mul_f32_e32 v213, 0xbfb8aa3b, v121
	v_mul_f32_e32 v248, 0xbfb8aa3b, v122
	v_mul_f32_e32 v249, 0xbfb8aa3b, v123
	v_exp_f32_e32 v212, v212
	v_exp_f32_e32 v213, v213
	v_exp_f32_e32 v248, v248
	v_exp_f32_e32 v249, v249
	v_add_f32_e32 v212, 1.0, v212
	v_add_f32_e32 v213, 1.0, v213
	v_add_f32_e32 v248, 1.0, v248
	v_add_f32_e32 v249, 1.0, v249
	v_rcp_f32_e32 v212, v212
	v_rcp_f32_e32 v213, v213
	v_rcp_f32_e32 v248, v248
	v_rcp_f32_e32 v249, v249
	v_mul_f32_e32 v120, v120, v212
	v_mul_f32_e32 v121, v121, v213
	v_mul_f32_e32 v122, v122, v248
	v_mul_f32_e32 v123, v123, v249
	s_waitcnt vmcnt(26)
; #define LAS __attribute__((address_space(3)))
; __device__ __forceinline__ float siluf_(float x) { return x * __builtin_amdgcn_rcpf(1.f + __expf(-x)); }
; __device__ __forceinline__ void prologue_mod_item(const Args& a, LAS unsigned char* lds, int item, int tid) {
;     ...
;         for (int idx = tid; idx < 512 * NSEQ; idx += 512) { const int s = idx >> 9, kl = idx & 511, k = half * 512 + kl;
;             const float v = s < NPB ? a.in[6][s * DM + k] : a.in[7][(s - NPB) * DM + k];
;             sl[kl * NSEQ + s] = siluf_(v); }
;         __syncthreads();
; #pragma unroll 16
;         for (int kk = 0; kk < 64; ++kk) { const int kl = kp * 64 + kk;
;             const float w = __builtin_nontemporal_load(&W[(size_t)(half * 512 + kl) * (6 * DM) + n0 + col]);
;             const LAS f32x4* sp = (const LAS f32x4*)(sl + kl * NSEQ);
; #pragma unroll
;             for (int q = 0; q < NSEQ / 4; ++q) { const f32x4 sv = sp[q]; const f32x2 w2 = (f32x2){w, w};
;                 acc[2 * q] = __builtin_elementwise_fma((f32x2){sv[0], sv[1]}, w2, acc[2 * q]); acc[2 * q + 1] = __builtin_elementwise_fma((f32x2){sv[2], sv[3]}, w2, acc[2 * q + 1]); } }
	v_mul_f32_e32 v212, 0xbfb8aa3b, v124
	v_mul_f32_e32 v213, 0xbfb8aa3b, v125
	v_mul_f32_e32 v248, 0xbfb8aa3b, v126
	v_mul_f32_e32 v249, 0xbfb8aa3b, v127
	v_exp_f32_e32 v212, v212
	v_exp_f32_e32 v213, v213
	v_exp_f32_e32 v248, v248
	v_exp_f32_e32 v249, v249
	v_add_f32_e32 v212, 1.0, v212
	v_add_f32_e32 v213, 1.0, v213
	v_add_f32_e32 v248, 1.0, v248
	v_add_f32_e32 v249, 1.0, v249
	v_rcp_f32_e32 v212, v212
	v_rcp_f32_e32 v213, v213
	v_rcp_f32_e32 v248, v248
	v_rcp_f32_e32 v249, v249
	v_mul_f32_e32 v124, v124, v212
	v_mul_f32_e32 v125, v125, v213
	v_mul_f32_e32 v126, v126, v248
	v_mul_f32_e32 v127, v127, v249
	s_waitcnt vmcnt(25)
	v_mul_f32_e32 v212, 0xbfb8aa3b, v128
	v_mul_f32_e32 v213, 0xbfb8aa3b, v129
	v_mul_f32_e32 v248, 0xbfb8aa3b, v130
	v_mul_f32_e32 v249, 0xbfb8aa3b, v131
	v_exp_f32_e32 v212, v212
	v_exp_f32_e32 v213, v213
	v_exp_f32_e32 v248, v248
	v_exp_f32_e32 v249, v249
	v_add_f32_e32 v212, 1.0, v212
	v_add_f32_e32 v213, 1.0, v213
	v_add_f32_e32 v248, 1.0, v248
	v_add_f32_e32 v249, 1.0, v249
	v_rcp_f32_e32 v212, v212
	v_rcp_f32_e32 v213, v213
	v_rcp_f32_e32 v248, v248
	v_rcp_f32_e32 v249, v249
	v_mul_f32_e32 v128, v128, v212
	v_mul_f32_e32 v129, v129, v213
	v_mul_f32_e32 v130, v130, v248
	v_mul_f32_e32 v131, v131, v249
	s_waitcnt vmcnt(24)
	v_mul_f32_e32 v212, 0xbfb8aa3b, v132
	v_mul_f32_e32 v213, 0xbfb8aa3b, v133
	v_mul_f32_e32 v248, 0xbfb8aa3b, v134
	v_mul_f32_e32 v249, 0xbfb8aa3b, v135
	v_exp_f32_e32 v212, v212
	v_exp_f32_e32 v213, v213
	v_exp_f32_e32 v248, v248
	v_exp_f32_e32 v249, v249
	v_add_f32_e32 v212, 1.0, v212
	v_add_f32_e32 v213, 1.0, v213
	v_add_f32_e32 v248, 1.0, v248
	v_add_f32_e32 v249, 1.0, v249
	v_rcp_f32_e32 v212, v212
	v_rcp_f32_e32 v213, v213
	v_rcp_f32_e32 v248, v248
	v_rcp_f32_e32 v249, v249
	v_mul_f32_e32 v132, v132, v212
	v_mul_f32_e32 v133, v133, v213
	v_mul_f32_e32 v134, v134, v248
	v_mul_f32_e32 v135, v135, v249
	s_waitcnt vmcnt(23)
	v_mul_f32_e32 v212, 0xbfb8aa3b, v136
	v_mul_f32_e32 v213, 0xbfb8aa3b, v137
	v_mul_f32_e32 v248, 0xbfb8aa3b, v138
	v_mul_f32_e32 v249, 0xbfb8aa3b, v139
	v_exp_f32_e32 v212, v212
	v_exp_f32_e32 v213, v213
	v_exp_f32_e32 v248, v248
	v_exp_f32_e32 v249, v249
	v_add_f32_e32 v212, 1.0, v212
	v_add_f32_e32 v213, 1.0, v213
	v_add_f32_e32 v248, 1.0, v248
	v_add_f32_e32 v249, 1.0, v249
	v_rcp_f32_e32 v212, v212
	v_rcp_f32_e32 v213, v213
	v_rcp_f32_e32 v248, v248
	v_rcp_f32_e32 v249, v249
	v_mul_f32_e32 v136, v136, v212
	v_mul_f32_e32 v137, v137, v213
	v_mul_f32_e32 v138, v138, v248
	v_mul_f32_e32 v139, v139, v249
	s_waitcnt vmcnt(22)
	v_mul_f32_e32 v212, 0xbfb8aa3b, v140
	v_mul_f32_e32 v213, 0xbfb8aa3b, v141
	v_mul_f32_e32 v248, 0xbfb8aa3b, v142
	v_mul_f32_e32 v249, 0xbfb8aa3b, v143
	v_exp_f32_e32 v212, v212
	v_exp_f32_e32 v213, v213
	v_exp_f32_e32 v248, v248
	v_exp_f32_e32 v249, v249
	v_add_f32_e32 v212, 1.0, v212
	v_add_f32_e32 v213, 1.0, v213
	v_add_f32_e32 v248, 1.0, v248
	v_add_f32_e32 v249, 1.0, v249
	v_rcp_f32_e32 v212, v212
	v_rcp_f32_e32 v213, v213
	v_rcp_f32_e32 v248, v248
	v_rcp_f32_e32 v249, v249
	v_mul_f32_e32 v140, v140, v212
	v_mul_f32_e32 v141, v141, v213
	v_mul_f32_e32 v142, v142, v248
	v_mul_f32_e32 v143, v143, v249
	s_waitcnt vmcnt(21)
	v_mfma_f32_16x16x4_f32 v[62:65], v120, v168, v[62:65]
	v_mfma_f32_16x16x4_f32 v[66:69], v120, v169, v[66:69]
	v_mfma_f32_16x16x4_f32 v[70:73], v120, v170, v[70:73]
	v_mfma_f32_16x16x4_f32 v[78:81], v128, v168, v[78:81]
	v_mfma_f32_16x16x4_f32 v[82:85], v128, v169, v[82:85]
	v_mfma_f32_16x16x4_f32 v[86:89], v128, v170, v[86:89]
	v_mfma_f32_16x16x4_f32 v[98:101], v136, v168, v[98:101]
	v_mfma_f32_16x16x4_f32 v[102:105], v136, v169, v[102:105]
	v_mfma_f32_16x16x4_f32 v[106:109], v136, v170, v[106:109]
	s_waitcnt vmcnt(20)
	v_mfma_f32_16x16x4_f32 v[62:65], v121, v172, v[62:65]
	v_mfma_f32_16x16x4_f32 v[66:69], v121, v173, v[66:69]
	v_mfma_f32_16x16x4_f32 v[70:73], v121, v174, v[70:73]
	v_mfma_f32_16x16x4_f32 v[78:81], v129, v172, v[78:81]
	v_mfma_f32_16x16x4_f32 v[82:85], v129, v173, v[82:85]
	v_mfma_f32_16x16x4_f32 v[86:89], v129, v174, v[86:89]
	v_mfma_f32_16x16x4_f32 v[98:101], v137, v172, v[98:101]
	v_mfma_f32_16x16x4_f32 v[102:105], v137, v173, v[102:105]
	v_mfma_f32_16x16x4_f32 v[106:109], v137, v174, v[106:109]
	s_waitcnt vmcnt(19)
	v_mfma_f32_16x16x4_f32 v[62:65], v122, v176, v[62:65]
	v_mfma_f32_16x16x4_f32 v[66:69], v122, v177, v[66:69]
	v_mfma_f32_16x16x4_f32 v[70:73], v122, v178, v[70:73]
	v_mfma_f32_16x16x4_f32 v[78:81], v130, v176, v[78:81]
	v_mfma_f32_16x16x4_f32 v[82:85], v130, v177, v[82:85]
	v_mfma_f32_16x16x4_f32 v[86:89], v130, v178, v[86:89]
	v_mfma_f32_16x16x4_f32 v[98:101], v138, v176, v[98:101]
	v_mfma_f32_16x16x4_f32 v[102:105], v138, v177, v[102:105]
	v_mfma_f32_16x16x4_f32 v[106:109], v138, v178, v[106:109]
	s_waitcnt vmcnt(18)
	v_mfma_f32_16x16x4_f32 v[62:65], v123, v180, v[62:65]
	v_mfma_f32_16x16x4_f32 v[66:69], v123, v181, v[66:69]
	v_mfma_f32_16x16x4_f32 v[70:73], v123, v182, v[70:73]
	v_mfma_f32_16x16x4_f32 v[78:81], v131, v180, v[78:81]
	v_mfma_f32_16x16x4_f32 v[82:85], v131, v181, v[82:85]
	v_mfma_f32_16x16x4_f32 v[86:89], v131, v182, v[86:89]
	v_mfma_f32_16x16x4_f32 v[98:101], v139, v180, v[98:101]
	v_mfma_f32_16x16x4_f32 v[102:105], v139, v181, v[102:105]
	v_mfma_f32_16x16x4_f32 v[106:109], v139, v182, v[106:109]
	s_waitcnt vmcnt(17)
	v_mfma_f32_16x16x4_f32 v[62:65], v124, v184, v[62:65]
	v_mfma_f32_16x16x4_f32 v[66:69], v124, v185, v[66:69]
	v_mfma_f32_16x16x4_f32 v[70:73], v124, v186, v[70:73]
	v_mfma_f32_16x16x4_f32 v[78:81], v132, v184, v[78:81]
	v_mfma_f32_16x16x4_f32 v[82:85], v132, v185, v[82:85]
	v_mfma_f32_16x16x4_f32 v[86:89], v132, v186, v[86:89]
	v_mfma_f32_16x16x4_f32 v[98:101], v140, v184, v[98:101]
	v_mfma_f32_16x16x4_f32 v[102:105], v140, v185, v[102:105]
	v_mfma_f32_16x16x4_f32 v[106:109], v140, v186, v[106:109]
	s_waitcnt vmcnt(16)
; #define LAS __attribute__((address_space(3)))
; __device__ __forceinline__ float siluf_(float x) { return x * __builtin_amdgcn_rcpf(1.f + __expf(-x)); }
; __device__ __forceinline__ void prologue_mod_item(const Args& a, LAS unsigned char* lds, int item, int tid) {
;     ...
;         for (int idx = tid; idx < 512 * NSEQ; idx += 512) { const int s = idx >> 9, kl = idx & 511, k = half * 512 + kl;
;             const float v = s < NPB ? a.in[6][s * DM + k] : a.in[7][(s - NPB) * DM + k];
;             sl[kl * NSEQ + s] = siluf_(v); }
;         __syncthreads();
; #pragma unroll 16
;         for (int kk = 0; kk < 64; ++kk) { const int kl = kp * 64 + kk;
;             const float w = __builtin_nontemporal_load(&W[(size_t)(half * 512 + kl) * (6 * DM) + n0 + col]);
;             const LAS f32x4* sp = (const LAS f32x4*)(sl + kl * NSEQ);
; #pragma unroll
;             for (int q = 0; q < NSEQ / 4; ++q) { const f32x4 sv = sp[q]; const f32x2 w2 = (f32x2){w, w};
;                 acc[2 * q] = __builtin_elementwise_fma((f32x2){sv[0], sv[1]}, w2, acc[2 * q]); acc[2 * q + 1] = __builtin_elementwise_fma((f32x2){sv[2], sv[3]}, w2, acc[2 * q + 1]); } }
	v_mfma_f32_16x16x4_f32 v[62:65], v125, v188, v[62:65]
	v_mfma_f32_16x16x4_f32 v[66:69], v125, v189, v[66:69]
	v_mfma_f32_16x16x4_f32 v[70:73], v125, v190, v[70:73]
	v_mfma_f32_16x16x4_f32 v[78:81], v133, v188, v[78:81]
	v_mfma_f32_16x16x4_f32 v[82:85], v133, v189, v[82:85]
	v_mfma_f32_16x16x4_f32 v[86:89], v133, v190, v[86:89]
	v_mfma_f32_16x16x4_f32 v[98:101], v141, v188, v[98:101]
	v_mfma_f32_16x16x4_f32 v[102:105], v141, v189, v[102:105]
	v_mfma_f32_16x16x4_f32 v[106:109], v141, v190, v[106:109]
	s_waitcnt vmcnt(15)
	v_mfma_f32_16x16x4_f32 v[62:65], v126, v192, v[62:65]
	v_mfma_f32_16x16x4_f32 v[66:69], v126, v193, v[66:69]
	v_mfma_f32_16x16x4_f32 v[70:73], v126, v194, v[70:73]
	v_mfma_f32_16x16x4_f32 v[78:81], v134, v192, v[78:81]
	v_mfma_f32_16x16x4_f32 v[82:85], v134, v193, v[82:85]
	v_mfma_f32_16x16x4_f32 v[86:89], v134, v194, v[86:89]
	v_mfma_f32_16x16x4_f32 v[98:101], v142, v192, v[98:101]
	v_mfma_f32_16x16x4_f32 v[102:105], v142, v193, v[102:105]
	v_mfma_f32_16x16x4_f32 v[106:109], v142, v194, v[106:109]
	s_waitcnt vmcnt(14)
	v_mfma_f32_16x16x4_f32 v[62:65], v127, v196, v[62:65]
	v_mfma_f32_16x16x4_f32 v[66:69], v127, v197, v[66:69]
	v_mfma_f32_16x16x4_f32 v[70:73], v127, v198, v[70:73]
	v_mfma_f32_16x16x4_f32 v[78:81], v135, v196, v[78:81]
	v_mfma_f32_16x16x4_f32 v[82:85], v135, v197, v[82:85]
	v_mfma_f32_16x16x4_f32 v[86:89], v135, v198, v[86:89]
	v_mfma_f32_16x16x4_f32 v[98:101], v143, v196, v[98:101]
	v_mfma_f32_16x16x4_f32 v[102:105], v143, v197, v[102:105]
	v_mfma_f32_16x16x4_f32 v[106:109], v143, v198, v[106:109]
	s_waitcnt vmcnt(13)
	v_mul_f32_e32 v212, 0xbfb8aa3b, v148
	v_mul_f32_e32 v213, 0xbfb8aa3b, v149
	v_mul_f32_e32 v248, 0xbfb8aa3b, v150
	v_mul_f32_e32 v249, 0xbfb8aa3b, v151
	v_exp_f32_e32 v212, v212
	v_exp_f32_e32 v213, v213
	v_exp_f32_e32 v248, v248
	v_exp_f32_e32 v249, v249
	v_add_f32_e32 v212, 1.0, v212
	v_add_f32_e32 v213, 1.0, v213
	v_add_f32_e32 v248, 1.0, v248
	v_add_f32_e32 v249, 1.0, v249
	v_rcp_f32_e32 v212, v212
	v_rcp_f32_e32 v213, v213
	v_rcp_f32_e32 v248, v248
	v_rcp_f32_e32 v249, v249
	v_mul_f32_e32 v148, v148, v212
	v_mul_f32_e32 v149, v149, v213
	v_mul_f32_e32 v150, v150, v248
	v_mul_f32_e32 v151, v151, v249
	s_waitcnt vmcnt(12)
	v_mul_f32_e32 v212, 0xbfb8aa3b, v152
	v_mul_f32_e32 v213, 0xbfb8aa3b, v153
	v_mul_f32_e32 v248, 0xbfb8aa3b, v154
	v_mul_f32_e32 v249, 0xbfb8aa3b, v155
	v_exp_f32_e32 v212, v212
	v_exp_f32_e32 v213, v213
	v_exp_f32_e32 v248, v248
	v_exp_f32_e32 v249, v249
	v_add_f32_e32 v212, 1.0, v212
	v_add_f32_e32 v213, 1.0, v213
	v_add_f32_e32 v248, 1.0, v248
	v_add_f32_e32 v249, 1.0, v249
	v_rcp_f32_e32 v212, v212
	v_rcp_f32_e32 v213, v213
	v_rcp_f32_e32 v248, v248
	v_rcp_f32_e32 v249, v249
	v_mul_f32_e32 v152, v152, v212
	v_mul_f32_e32 v153, v153, v213
	v_mul_f32_e32 v154, v154, v248
	v_mul_f32_e32 v155, v155, v249
	s_waitcnt vmcnt(11)
	v_mul_f32_e32 v212, 0xbfb8aa3b, v156
	v_mul_f32_e32 v213, 0xbfb8aa3b, v157
	v_mul_f32_e32 v248, 0xbfb8aa3b, v158
	v_mul_f32_e32 v249, 0xbfb8aa3b, v159
	v_exp_f32_e32 v212, v212
	v_exp_f32_e32 v213, v213
	v_exp_f32_e32 v248, v248
	v_exp_f32_e32 v249, v249
	v_add_f32_e32 v212, 1.0, v212
	v_add_f32_e32 v213, 1.0, v213
	v_add_f32_e32 v248, 1.0, v248
	v_add_f32_e32 v249, 1.0, v249
	v_rcp_f32_e32 v212, v212
	v_rcp_f32_e32 v213, v213
	v_rcp_f32_e32 v248, v248
	v_rcp_f32_e32 v249, v249
	v_mul_f32_e32 v156, v156, v212
	v_mul_f32_e32 v157, v157, v213
	v_mul_f32_e32 v158, v158, v248
	v_mul_f32_e32 v159, v159, v249
	s_waitcnt vmcnt(10)
	v_mul_f32_e32 v212, 0xbfb8aa3b, v160
	v_mul_f32_e32 v213, 0xbfb8aa3b, v161
	v_mul_f32_e32 v248, 0xbfb8aa3b, v162
	v_mul_f32_e32 v249, 0xbfb8aa3b, v163
	v_exp_f32_e32 v212, v212
	v_exp_f32_e32 v213, v213
	v_exp_f32_e32 v248, v248
	v_exp_f32_e32 v249, v249
	v_add_f32_e32 v212, 1.0, v212
	v_add_f32_e32 v213, 1.0, v213
	v_add_f32_e32 v248, 1.0, v248
	v_add_f32_e32 v249, 1.0, v249
	v_rcp_f32_e32 v212, v212
	v_rcp_f32_e32 v213, v213
	v_rcp_f32_e32 v248, v248
	v_rcp_f32_e32 v249, v249
	v_mul_f32_e32 v160, v160, v212
	v_mul_f32_e32 v161, v161, v213
	v_mul_f32_e32 v162, v162, v248
	v_mul_f32_e32 v163, v163, v249
	s_waitcnt vmcnt(9)
	v_mul_f32_e32 v212, 0xbfb8aa3b, v34
	v_mul_f32_e32 v213, 0xbfb8aa3b, v35
	v_mul_f32_e32 v248, 0xbfb8aa3b, v36
	v_mul_f32_e32 v249, 0xbfb8aa3b, v37
	v_exp_f32_e32 v212, v212
	v_exp_f32_e32 v213, v213
	v_exp_f32_e32 v248, v248
	v_exp_f32_e32 v249, v249
	v_add_f32_e32 v212, 1.0, v212
	v_add_f32_e32 v213, 1.0, v213
	v_add_f32_e32 v248, 1.0, v248
	v_add_f32_e32 v249, 1.0, v249
	v_rcp_f32_e32 v212, v212
	v_rcp_f32_e32 v213, v213
	v_rcp_f32_e32 v248, v248
	v_rcp_f32_e32 v249, v249
	v_mul_f32_e32 v34, v34, v212
	v_mul_f32_e32 v35, v35, v213
	v_mul_f32_e32 v36, v36, v248
	v_mul_f32_e32 v37, v37, v249
	s_waitcnt vmcnt(8)
	v_mul_f32_e32 v212, 0xbfb8aa3b, v38
	v_mul_f32_e32 v213, 0xbfb8aa3b, v39
	v_mul_f32_e32 v248, 0xbfb8aa3b, v40
	v_mul_f32_e32 v249, 0xbfb8aa3b, v41
	v_exp_f32_e32 v212, v212
	v_exp_f32_e32 v213, v213
	v_exp_f32_e32 v248, v248
	v_exp_f32_e32 v249, v249
	v_add_f32_e32 v212, 1.0, v212
	v_add_f32_e32 v213, 1.0, v213
	v_add_f32_e32 v248, 1.0, v248
	v_add_f32_e32 v249, 1.0, v249
	v_rcp_f32_e32 v212, v212
	v_rcp_f32_e32 v213, v213
	v_rcp_f32_e32 v248, v248
	v_rcp_f32_e32 v249, v249
	v_mul_f32_e32 v38, v38, v212
	v_mul_f32_e32 v39, v39, v213
	v_mul_f32_e32 v40, v40, v248
	v_mul_f32_e32 v41, v41, v249
	s_waitcnt vmcnt(7)
	v_mfma_f32_16x16x4_f32 v[62:65], v148, v216, v[62:65]
	v_mfma_f32_16x16x4_f32 v[66:69], v148, v217, v[66:69]
	v_mfma_f32_16x16x4_f32 v[70:73], v148, v218, v[70:73]
	v_mfma_f32_16x16x4_f32 v[78:81], v156, v216, v[78:81]
	v_mfma_f32_16x16x4_f32 v[82:85], v156, v217, v[82:85]
	v_mfma_f32_16x16x4_f32 v[86:89], v156, v218, v[86:89]
	v_mfma_f32_16x16x4_f32 v[98:101], v34, v216, v[98:101]
	v_mfma_f32_16x16x4_f32 v[102:105], v34, v217, v[102:105]
	v_mfma_f32_16x16x4_f32 v[106:109], v34, v218, v[106:109]
	s_waitcnt vmcnt(6)
; #define LAS __attribute__((address_space(3)))
; __device__ __forceinline__ void prologue_mod_item(const Args& a, LAS unsigned char* lds, int item, int tid) {
;     ...
;         for (int kk = 0; kk < 64; ++kk) { const int kl = kp * 64 + kk;
;             const float w = __builtin_nontemporal_load(&W[(size_t)(half * 512 + kl) * (6 * DM) + n0 + col]);
;             const LAS f32x4* sp = (const LAS f32x4*)(sl + kl * NSEQ);
; #pragma unroll
;             for (int q = 0; q < NSEQ / 4; ++q) { const f32x4 sv = sp[q]; const f32x2 w2 = (f32x2){w, w};
;                 acc[2 * q] = __builtin_elementwise_fma((f32x2){sv[0], sv[1]}, w2, acc[2 * q]); acc[2 * q + 1] = __builtin_elementwise_fma((f32x2){sv[2], sv[3]}, w2, acc[2 * q + 1]); } }
;     }
;     __syncthreads();
; #pragma unroll
;     for (int s = 0; s < NSEQ; ++s) sl[(kp * NSEQ + s) * 64 + col] = acc[s >> 1][s & 1];
	v_mfma_f32_16x16x4_f32 v[62:65], v149, v220, v[62:65]
	v_mfma_f32_16x16x4_f32 v[66:69], v149, v221, v[66:69]
	v_mfma_f32_16x16x4_f32 v[70:73], v149, v222, v[70:73]
	v_mfma_f32_16x16x4_f32 v[78:81], v157, v220, v[78:81]
	v_mfma_f32_16x16x4_f32 v[82:85], v157, v221, v[82:85]
	v_mfma_f32_16x16x4_f32 v[86:89], v157, v222, v[86:89]
	v_mfma_f32_16x16x4_f32 v[98:101], v35, v220, v[98:101]
	v_mfma_f32_16x16x4_f32 v[102:105], v35, v221, v[102:105]
	v_mfma_f32_16x16x4_f32 v[106:109], v35, v222, v[106:109]
	s_waitcnt vmcnt(5)
	v_mfma_f32_16x16x4_f32 v[62:65], v150, v224, v[62:65]
	v_mfma_f32_16x16x4_f32 v[66:69], v150, v225, v[66:69]
	v_mfma_f32_16x16x4_f32 v[70:73], v150, v226, v[70:73]
	v_mfma_f32_16x16x4_f32 v[78:81], v158, v224, v[78:81]
	v_mfma_f32_16x16x4_f32 v[82:85], v158, v225, v[82:85]
	v_mfma_f32_16x16x4_f32 v[86:89], v158, v226, v[86:89]
	v_mfma_f32_16x16x4_f32 v[98:101], v36, v224, v[98:101]
	v_mfma_f32_16x16x4_f32 v[102:105], v36, v225, v[102:105]
	v_mfma_f32_16x16x4_f32 v[106:109], v36, v226, v[106:109]
	s_waitcnt vmcnt(4)
	v_mfma_f32_16x16x4_f32 v[62:65], v151, v228, v[62:65]
	v_mfma_f32_16x16x4_f32 v[66:69], v151, v229, v[66:69]
	v_mfma_f32_16x16x4_f32 v[70:73], v151, v230, v[70:73]
	v_mfma_f32_16x16x4_f32 v[78:81], v159, v228, v[78:81]
	v_mfma_f32_16x16x4_f32 v[82:85], v159, v229, v[82:85]
	v_mfma_f32_16x16x4_f32 v[86:89], v159, v230, v[86:89]
	v_mfma_f32_16x16x4_f32 v[98:101], v37, v228, v[98:101]
	v_mfma_f32_16x16x4_f32 v[102:105], v37, v229, v[102:105]
	v_mfma_f32_16x16x4_f32 v[106:109], v37, v230, v[106:109]
	s_waitcnt vmcnt(3)
	v_mfma_f32_16x16x4_f32 v[62:65], v152, v232, v[62:65]
	v_mfma_f32_16x16x4_f32 v[66:69], v152, v233, v[66:69]
	v_mfma_f32_16x16x4_f32 v[70:73], v152, v234, v[70:73]
	v_mfma_f32_16x16x4_f32 v[78:81], v160, v232, v[78:81]
	v_mfma_f32_16x16x4_f32 v[82:85], v160, v233, v[82:85]
	v_mfma_f32_16x16x4_f32 v[86:89], v160, v234, v[86:89]
	v_mfma_f32_16x16x4_f32 v[98:101], v38, v232, v[98:101]
	v_mfma_f32_16x16x4_f32 v[102:105], v38, v233, v[102:105]
	v_mfma_f32_16x16x4_f32 v[106:109], v38, v234, v[106:109]
	s_waitcnt vmcnt(2)
	v_mfma_f32_16x16x4_f32 v[62:65], v153, v236, v[62:65]
	v_mfma_f32_16x16x4_f32 v[66:69], v153, v237, v[66:69]
	v_mfma_f32_16x16x4_f32 v[70:73], v153, v238, v[70:73]
	v_mfma_f32_16x16x4_f32 v[78:81], v161, v236, v[78:81]
	v_mfma_f32_16x16x4_f32 v[82:85], v161, v237, v[82:85]
	v_mfma_f32_16x16x4_f32 v[86:89], v161, v238, v[86:89]
	v_mfma_f32_16x16x4_f32 v[98:101], v39, v236, v[98:101]
	v_mfma_f32_16x16x4_f32 v[102:105], v39, v237, v[102:105]
	v_mfma_f32_16x16x4_f32 v[106:109], v39, v238, v[106:109]
	s_waitcnt vmcnt(1)
	v_mfma_f32_16x16x4_f32 v[62:65], v154, v240, v[62:65]
	v_mfma_f32_16x16x4_f32 v[66:69], v154, v241, v[66:69]
	v_mfma_f32_16x16x4_f32 v[70:73], v154, v242, v[70:73]
	v_mfma_f32_16x16x4_f32 v[78:81], v162, v240, v[78:81]
	v_mfma_f32_16x16x4_f32 v[82:85], v162, v241, v[82:85]
	v_mfma_f32_16x16x4_f32 v[86:89], v162, v242, v[86:89]
	v_mfma_f32_16x16x4_f32 v[98:101], v40, v240, v[98:101]
	v_mfma_f32_16x16x4_f32 v[102:105], v40, v241, v[102:105]
	v_mfma_f32_16x16x4_f32 v[106:109], v40, v242, v[106:109]
	s_waitcnt vmcnt(0)
	v_mfma_f32_16x16x4_f32 v[62:65], v155, v244, v[62:65]
	v_mfma_f32_16x16x4_f32 v[66:69], v155, v245, v[66:69]
	v_mfma_f32_16x16x4_f32 v[70:73], v155, v246, v[70:73]
	v_mfma_f32_16x16x4_f32 v[78:81], v163, v244, v[78:81]
	v_mfma_f32_16x16x4_f32 v[82:85], v163, v245, v[82:85]
	v_mfma_f32_16x16x4_f32 v[86:89], v163, v246, v[86:89]
	v_mfma_f32_16x16x4_f32 v[98:101], v41, v244, v[98:101]
	v_mfma_f32_16x16x4_f32 v[102:105], v41, v245, v[102:105]
	v_mfma_f32_16x16x4_f32 v[106:109], v41, v246, v[106:109]
	s_nop 11
	s_barrier
	ds_write_b128 v207, v[62:65]
	ds_write_b128 v207, v[66:69] offset:208
	ds_write_b128 v207, v[70:73] offset:416
	ds_write_b128 v207, v[78:81] offset:64
	ds_write_b128 v207, v[82:85] offset:272
	ds_write_b128 v207, v[86:89] offset:480
	ds_write_b128 v207, v[98:101] offset:128
	ds_write_b128 v207, v[102:105] offset:336
	ds_write_b128 v207, v[106:109] offset:544
	s_waitcnt lgkmcnt(0)
	s_barrier
; __device__ __forceinline__ void prologue_mod_item(const Args& a, LAS unsigned char* lds, int item, int tid) {
;     ...
; #pragma unroll
;     for (int s = 0; s < NSEQ; ++s) sl[(kp * NSEQ + s) * 64 + col] = acc[s >> 1][s & 1];
;     __syncthreads();
;     float* mod = (float*)(a.ws + WS_MOD) + (size_t)l * NSEQ * (6 * DM);
;     for (int o = tid; o < NSEQ * 64; o += 512) { const int s = o >> 6, c = o & 63; float v = a.in[10][l * (6 * DM) + n0 + c];
; #pragma unroll
;         for (int p = 0; p < 8; ++p) v += sl[(p * NSEQ + s) * 64 + c];
;         mod[(size_t)s * (6 * DM) + n0 + c] = v; }
;     __syncthreads();
	s_mov_b32 exec_hi, 0xffff
	ds_read_b128 v[168:171], v208
	ds_read_b128 v[172:175], v208 offset:9984
	ds_read_b128 v[176:179], v208 offset:19968
	ds_read_b128 v[180:183], v208 offset:29952
	ds_read_b128 v[184:187], v209
	ds_read_b128 v[188:191], v209 offset:9984
	ds_read_b128 v[192:195], v209 offset:19968
	ds_read_b128 v[196:199], v209 offset:29952
	s_waitcnt lgkmcnt(7)
	v_add_f32_e32 v250, v211, v168
	v_add_f32_e32 v251, v211, v169
	v_add_f32_e32 v42, v211, v170
	v_add_f32_e32 v43, v211, v171
	s_waitcnt lgkmcnt(6)
	v_add_f32_e32 v250, v250, v172
	v_add_f32_e32 v251, v251, v173
	v_add_f32_e32 v42, v42, v174
	v_add_f32_e32 v43, v43, v175
	s_waitcnt lgkmcnt(5)
	v_add_f32_e32 v250, v250, v176
	v_add_f32_e32 v251, v251, v177
	v_add_f32_e32 v42, v42, v178
	v_add_f32_e32 v43, v43, v179
	s_waitcnt lgkmcnt(4)
	v_add_f32_e32 v250, v250, v180
	v_add_f32_e32 v251, v251, v181
	v_add_f32_e32 v42, v42, v182
	v_add_f32_e32 v43, v43, v183
	s_waitcnt lgkmcnt(3)
	v_add_f32_e32 v250, v250, v184
	v_add_f32_e32 v251, v251, v185
	v_add_f32_e32 v42, v42, v186
	v_add_f32_e32 v43, v43, v187
	s_waitcnt lgkmcnt(2)
	v_add_f32_e32 v250, v250, v188
	v_add_f32_e32 v251, v251, v189
	v_add_f32_e32 v42, v42, v190
	v_add_f32_e32 v43, v43, v191
	s_waitcnt lgkmcnt(1)
	v_add_f32_e32 v250, v250, v192
	v_add_f32_e32 v251, v251, v193
	v_add_f32_e32 v42, v42, v194
	v_add_f32_e32 v43, v43, v195
	s_waitcnt lgkmcnt(0)
	v_add_f32_e32 v250, v250, v196
	v_add_f32_e32 v251, v251, v197
	v_add_f32_e32 v42, v42, v198
	v_add_f32_e32 v43, v43, v199
	s_mov_b32 s12, s10
	s_mov_b32 s13, s11
	global_store_dword v210, v250, s[12:13]
	s_add_u32 s12, s12, 0x6000
	s_addc_u32 s13, s13, 0
	global_store_dword v210, v251, s[12:13]
	s_add_u32 s12, s12, 0x6000
	s_addc_u32 s13, s13, 0
	global_store_dword v210, v42, s[12:13]
	s_add_u32 s12, s12, 0x6000
	s_addc_u32 s13, s13, 0
	global_store_dword v210, v43, s[12:13]
	s_cmp_gt_u32 s3, 3
	s_cbranch_scc1 .Lmod_red_done
	ds_read_b128 v[168:171], v208 offset:128
	ds_read_b128 v[172:175], v208 offset:10112
	ds_read_b128 v[176:179], v208 offset:20096
	ds_read_b128 v[180:183], v208 offset:30080
	ds_read_b128 v[184:187], v209 offset:128
	ds_read_b128 v[188:191], v209 offset:10112
	ds_read_b128 v[192:195], v209 offset:20096
	ds_read_b128 v[196:199], v209 offset:30080
	s_waitcnt lgkmcnt(7)
	v_add_f32_e32 v250, v211, v168
	v_add_f32_e32 v251, v211, v169
	v_add_f32_e32 v42, v211, v170
	v_add_f32_e32 v43, v211, v171
	s_waitcnt lgkmcnt(6)
	v_add_f32_e32 v250, v250, v172
	v_add_f32_e32 v251, v251, v173
	v_add_f32_e32 v42, v42, v174
	v_add_f32_e32 v43, v43, v175
	s_waitcnt lgkmcnt(5)
	v_add_f32_e32 v250, v250, v176
	v_add_f32_e32 v251, v251, v177
	v_add_f32_e32 v42, v42, v178
	v_add_f32_e32 v43, v43, v179
	s_waitcnt lgkmcnt(4)
	v_add_f32_e32 v250, v250, v180
	v_add_f32_e32 v251, v251, v181
	v_add_f32_e32 v42, v42, v182
	v_add_f32_e32 v43, v43, v183
	s_waitcnt lgkmcnt(3)
	v_add_f32_e32 v250, v250, v184
	v_add_f32_e32 v251, v251, v185
	v_add_f32_e32 v42, v42, v186
	v_add_f32_e32 v43, v43, v187
	s_waitcnt lgkmcnt(2)
	v_add_f32_e32 v250, v250, v188
	v_add_f32_e32 v251, v251, v189
	v_add_f32_e32 v42, v42, v190
	v_add_f32_e32 v43, v43, v191
	s_waitcnt lgkmcnt(1)
	v_add_f32_e32 v250, v250, v192
	v_add_f32_e32 v251, v251, v193
	v_add_f32_e32 v42, v42, v194
	v_add_f32_e32 v43, v43, v195
	s_waitcnt lgkmcnt(0)
	v_add_f32_e32 v250, v250, v196
	v_add_f32_e32 v251, v251, v197
	v_add_f32_e32 v42, v42, v198
	v_add_f32_e32 v43, v43, v199
	s_add_u32 s12, s10, 0xc0000
	s_addc_u32 s13, s11, 0
	global_store_dword v210, v250, s[12:13]
	s_add_u32 s12, s12, 0x6000
	s_addc_u32 s13, s13, 0
	global_store_dword v210, v251, s[12:13]
	s_add_u32 s12, s12, 0x6000
	s_addc_u32 s13, s13, 0
	global_store_dword v210, v42, s[12:13]
	s_add_u32 s12, s12, 0x6000
	s_addc_u32 s13, s13, 0
	global_store_dword v210, v43, s[12:13]
.Lmod_red_done:
	s_mov_b64 exec, -1
	v_readlane_b32 s6, v252, 0
	s_add_i32 s15, s15, s6
	s_cmpk_gt_i32 s15, 0xff
	s_waitcnt vmcnt(0) lgkmcnt(0)
	s_barrier
	s_cbranch_scc0 .Lmod_item

; #define LAS __attribute__((address_space(3)))
; __device__ __forceinline__ unsigned pk2(float lo, float hi) { unsigned r; asm("v_cvt_pk_bf16_f32 %0, %1, %2" : "=v"(r) : "v"(lo), "v"(hi)); return r; }
; __device__ __forceinline__ bf16_t f2bf(float f) { return (bf16_t)(pk2(f, 0.f) & 0xffffu); }
; __device__ __forceinline__ void attn_item(const Args& a, LAS unsigned char* lds, int layer, bool is_sample, int b, int c, int kvh, int seq_row0, int nchunks, bf16_t* proj, const int tid) {
;     ...
;         u32x4 w; w.x = pk2(kf[0], kf[1]); w.y = pk2(kf[2], kf[3]); w.z = pk2(kf[4], kf[5]); w.w = pk2(kf[6], kf[7]);
;         *(LAS u32x4*)(lds + L_KS + kl * PK + oc * 16) = w;
; #pragma unroll
;         for (int e = 0; e < 8; ++e) *(LAS bf16_t*)(lds + L_VT + (oc * 8 + e) * PV + (kl ^ (oc << 2)) * 2) = f2bf(vf[e]);
;     }
;     LAS float* bt = (LAS float*)(lds + L_BT);
;     for (int idx = tid; idx < 1024; idx += 512) { const int g = idx >> 8, ri = idx & 255; const int rel = ri - 191;
;         int n = -rel; int ret = n < 0 ? 16 : 0; n = n < 0 ? -n : n;
;         int bk;
;         if (n < 8) bk = n; else if (n < 12) bk = 8; else if (n < 16) bk = 9; else if (n < 23) bk = 10; else if (n < 32) bk = 11; else if (n < 46) bk = 12; else if (n < 64) bk = 13; else if (n < 91) bk = 14; else bk = 15;
;         bt[idx] = a.in[8][(ret + bk) * NQH + kvh * 4 + g] * 1.4426950408889634f; }
.LBB0_467:
	s_or_b64 exec, exec, s[16:17]
	v_lshlrev_b32_e32 v0, 1, v35
	v_xor_b32_e32 v0, v0, v43
	v_cvt_pk_bf16_f32 v26, v26, v27
	v_cvt_pk_bf16_f32 v27, v28, v29
	v_cvt_pk_bf16_f32 v28, v30, v31
	v_mad_u64_u32 v[30:31], s[4:5], v35, s74, v[40:41]
	v_cvt_pk_bf16_f32 v18, v18, v1
	v_add3_u32 v0, 0, v0, v34
	v_cvt_pk_bf16_f32 v29, v32, v33
	ds_write_b128 v30, v[26:29]
	ds_write_b16 v0, v18 offset:27648
	v_cvt_pk_bf16_f32 v18, v19, v1
	ds_write_b16 v0, v18 offset:28048
	v_cvt_pk_bf16_f32 v18, v20, v1
	ds_write_b16 v0, v18 offset:28448
	v_cvt_pk_bf16_f32 v18, v21, v1
	ds_write_b16 v0, v18 offset:28848
	v_cvt_pk_bf16_f32 v18, v22, v1
	ds_write_b16 v0, v18 offset:29248
	v_cvt_pk_bf16_f32 v18, v23, v1
	s_movk_i32 s4, 0x400
	ds_write_b16 v0, v18 offset:29648
	v_cvt_pk_bf16_f32 v18, v24, v1
	v_cmp_gt_i32_e32 vcc, s4, v36
	ds_write_b16 v0, v18 offset:30048
	v_cvt_pk_bf16_f32 v18, v25, v1
	ds_write_b16 v0, v18 offset:30448
	v_readlane_b32 s6, v255, 36
	s_add_i32 s6, s6, 0x200
	s_cmp_lt_i32 s3, s6
	s_cselect_b64 vcc, vcc, 0
	s_and_saveexec_b64 s[4:5], vcc
	v_readlane_b32 s44, v252, 5
	s_movk_i32 s10, 0x1ff
	v_readlane_b32 s45, v252, 6
	v_readlane_b32 s46, v252, 7
	v_readlane_b32 s47, v252, 8
	v_readlane_b32 s48, v252, 9
	v_readlane_b32 s49, v252, 10
	v_readlane_b32 s50, v252, 11
	v_readlane_b32 s51, v252, 12
	v_readlane_b32 s52, v252, 13
	v_readlane_b32 s53, v252, 14
	v_readlane_b32 s54, v252, 15
	v_readlane_b32 s55, v252, 16
	v_readlane_b32 s56, v252, 17
	v_readlane_b32 s57, v252, 18
	v_readlane_b32 s58, v252, 19
	v_readlane_b32 s59, v252, 20
	s_cbranch_execz .LBB0_475
	s_movk_i32 s6, 0xff41
	v_add_u32_sdwa v0, v36, s6 dst_sel:DWORD dst_unused:UNUSED_PAD src0_sel:BYTE_0 src1_sel:DWORD
	s_movk_i32 s6, 0xbf
	v_sub_co_u32_sdwa v18, vcc, s6, v36 dst_sel:DWORD dst_unused:UNUSED_PAD src0_sel:DWORD src1_sel:BYTE_0
	s_movk_i32 s6, 0x5b
	s_nop 0
	v_cndmask_b32_e32 v0, v18, v0, vcc
	v_cndmask_b32_e64 v19, 0, 16, vcc
	v_cmp_gt_u32_e32 vcc, s6, v0
	v_min_i32_e32 v20, 8, v0
	s_mov_b64 s[14:15], -1
	v_cndmask_b32_e64 v18, 15, 14, vcc
	v_cmp_lt_u32_e32 vcc, 63, v0
	s_nop 1
	v_cndmask_b32_e32 v18, 13, v18, vcc
	v_cmp_gt_i32_e32 vcc, 12, v0
	s_nop 1
	v_cndmask_b32_e32 v20, 9, v20, vcc
	v_cmp_gt_i32_e32 vcc, 16, v0
	s_nop 1
	v_cndmask_b32_e32 v20, 10, v20, vcc
	v_cmp_gt_i32_e32 vcc, 23, v0
	s_nop 1
	v_cndmask_b32_e32 v20, 11, v20, vcc
	v_cmp_lt_u32_e32 vcc, 45, v0
	s_nop 1
	v_cndmask_b32_e32 v18, 12, v18, vcc
	v_cmp_gt_i32_e32 vcc, 32, v0
	s_nop 1
	v_cndmask_b32_e32 v0, v18, v20, vcc
	v_max_i32_e32 v18, 0x200, v36
	v_sub_u32_e32 v18, v18, v36
	v_add_u32_e32 v0, v0, v19
	v_add_u32_e32 v18, 0x1ff, v18
	v_lshl_or_b32 v0, v0, 4, s40
	v_cmp_lt_u32_e32 vcc, s10, v18
	v_mov_b32_e32 v19, v36
	s_and_saveexec_b64 s[6:7], vcc
	s_cbranch_execz .LBB0_472
	v_lshrrev_b32_e32 v18, 9, v18
	v_add_u32_e32 v18, 1, v18
	v_and_b32_e32 v22, 0xfffffe, v18
	v_readlane_b32 s10, v254, 43
	v_readlane_b32 s40, v252, 5
	v_mov_b32_e32 v19, v0
	v_lshl_add_u32 v23, v36, 2, s10
	s_mov_b64 s[14:15], 0
	v_mov_b32_e32 v24, v22
	v_mov_b64_e32 v[20:21], v[36:37]
	v_readlane_b32 s41, v252, 6
	s_mov_b32 s10, 0x3fb8aa3b
	v_readlane_b32 s42, v252, 7
	v_readlane_b32 s43, v252, 8
	v_readlane_b32 s44, v252, 9
	v_readlane_b32 s45, v252, 10
	v_readlane_b32 s46, v252, 11
	v_readlane_b32 s47, v252, 12
	v_readlane_b32 s48, v252, 13
	v_readlane_b32 s49, v252, 14
	v_readlane_b32 s50, v252, 15
	v_readlane_b32 s51, v252, 16
	v_readlane_b32 s52, v252, 17
	v_readlane_b32 s53, v252, 18
	v_readlane_b32 s54, v252, 19
	v_readlane_b32 s55, v252, 20
